# F1: third round of 16 tiles replaced by 256 per-workgroup 64x64 sub-blocks (K split over waves, LDS reduce)
# baseline (speedup 1.0000x reference)
.LBB0_7:
	v_readlane_b32 s0, v252, 7
	s_cmp_le_i32 s0, s56
	s_cbranch_scc1 .LBB0_1418
	v_readlane_b32 s0, v252, 7
	s_cmp_lt_i32 s0, 0x186a1
	s_cselect_b64 s[0:1], -1, 0
	v_writelane_b32 v252, s0, 8
	v_and_b32_e32 v202, 0x3ff, v0
	v_and_b32_e32 v0, 0x3fffffff, v0
	v_writelane_b32 v252, s1, 9
	s_add_u32 s0, s12, 0x12cd8200
	s_addc_u32 s1, s13, 0
	v_writelane_b32 v252, s0, 10
	v_cmp_eq_u32_e64 s[92:93], 0, v202
	v_mbcnt_lo_u32_b32 v2, -1, 0
	v_writelane_b32 v252, s1, 11
	s_add_u32 s0, s12, 0x12cd8400
	s_addc_u32 s1, s13, 0
	v_writelane_b32 v252, s0, 12
	v_mov_b32_e32 v1, 0
	v_mov_b64_e32 v[170:171], 0x200
	v_writelane_b32 v252, s1, 13
	s_add_u32 s0, s12, 0x12cd8500
	s_addc_u32 s1, s13, 0
	v_writelane_b32 v252, s0, 14
	v_mov_b64_e32 v[172:173], 0x1ff
	v_mov_b32_e32 v203, 0x358637bd
	v_writelane_b32 v252, s1, 15
	s_add_u32 s0, s12, 0x12cd8600
	s_addc_u32 s1, s13, 0
	v_writelane_b32 v252, s0, 16
	v_mov_b32_e32 v204, 0x3ecc95a3
	v_mov_b32_e32 v205, 0x38d1b717
	v_writelane_b32 v252, s1, 17
	s_add_u32 s0, s12, 0x12cd8700
	s_addc_u32 s1, s13, 0
	v_writelane_b32 v252, s0, 18
	v_mov_b32_e32 v206, 0xc0447cbd
	v_mov_b32_e32 v207, 1
	v_writelane_b32 v252, s1, 19
	s_add_u32 s0, s12, 0x12cd8800
	s_addc_u32 s1, s13, 0
	v_writelane_b32 v252, s0, 20
	v_not_b32_e32 v208, 63
	v_mov_b32_e32 v209, 0x42800000
	v_writelane_b32 v252, s1, 21
	s_add_u32 s0, s12, 0x12cd8900
	s_addc_u32 s1, s13, 0
	v_writelane_b32 v252, s0, 22
	v_mbcnt_hi_u32_b32 v210, -1, v2
	v_mov_b32_e32 v211, 0x7f800000
	v_writelane_b32 v252, s1, 23
	s_add_u32 s0, s12, 0x12cd8a00
	s_addc_u32 s1, s13, 0
	v_writelane_b32 v252, s0, 24
	v_mov_b32_e32 v212, 0x7fc00000
	v_mov_b32_e32 v213, 0xff800000
	v_writelane_b32 v252, s1, 25
	s_add_u32 s0, s12, 0x12cd8b00
	s_addc_u32 s1, s13, 0
	v_writelane_b32 v252, s0, 26
	v_mov_b32_e32 v174, 0x3f317218
	v_mov_b32_e32 v214, 2
	v_writelane_b32 v252, s1, 27
	s_add_u32 s0, s12, 0x12cd8c00
	s_addc_u32 s1, s13, 0
	v_writelane_b32 v252, s0, 28
	v_mov_b32_e32 v215, 0xff60
	v_mov_b32_e32 v216, 0xff5c
	v_writelane_b32 v252, s1, 29
	s_add_u32 s0, s12, 0x12cd8d00
	s_addc_u32 s1, s13, 0
	v_writelane_b32 v252, s0, 30
	v_mov_b32_e32 v217, 0xff1c
	v_mov_b32_e32 v218, 0xfdbc
	v_writelane_b32 v252, s1, 31
	s_add_u32 s0, s12, 0x12cd8e00
	s_addc_u32 s1, s13, 0
	v_writelane_b32 v252, s0, 32
	v_mov_b32_e32 v219, 30
	v_mov_b32_e32 v220, 6
	v_writelane_b32 v252, s1, 33
	s_add_u32 s0, s12, 0x12cd8f00
	s_addc_u32 s1, s13, 0
	v_writelane_b32 v252, s0, 34
	v_mov_b32_e32 v221, 5
	v_mov_b32_e32 v222, 24
	v_writelane_b32 v252, s1, 35
	s_add_u32 s0, s12, 0x12cd9000
	s_addc_u32 s1, s13, 0
	v_writelane_b32 v252, s0, 36
	v_mov_b32_e32 v223, 8
	v_mov_b32_e32 v224, 0x100
	v_writelane_b32 v252, s1, 37
	s_add_u32 s0, s12, 0x12cd9100
	s_addc_u32 s1, s13, 0
	v_writelane_b32 v252, s0, 38
	v_mov_b32_e32 v225, 0x400
	v_mov_b32_e32 v226, 0x80000
	v_writelane_b32 v252, s1, 39
	s_add_u32 s0, s12, 0x12cd9200
	s_addc_u32 s1, s13, 0
	v_writelane_b32 v252, s0, 40
	s_mov_b32 s57, 0xe0000
	s_movk_i32 s85, 0x2000
	v_writelane_b32 v252, s1, 41
	s_add_u32 s0, s12, 0x12cd9300
	s_addc_u32 s1, s13, 0
	v_writelane_b32 v252, s0, 42
	s_cmp_eq_u32 s8, 15
	s_movk_i32 s29, 0x210
	v_writelane_b32 v252, s1, 43
	s_cselect_b64 s[0:1], -1, 0
	v_writelane_b32 v252, s0, 44
	s_cmp_eq_u32 s8, 14
	s_mov_b32 s90, 0xbfb8aa3b
	v_writelane_b32 v252, s1, 45
	s_cselect_b64 s[0:1], -1, 0
	v_writelane_b32 v252, s0, 46
	s_cmp_eq_u32 s8, 13
	s_movk_i32 s84, 0x104
	v_writelane_b32 v252, s1, 47
	s_cselect_b64 s[0:1], -1, 0
	v_writelane_b32 v252, s0, 48
	s_cmp_eq_u32 s8, 12
	s_movk_i32 s37, 0x1000
	v_writelane_b32 v252, s1, 49
	s_cselect_b64 s[0:1], -1, 0
	v_writelane_b32 v252, s0, 50
	s_cmp_eq_u32 s8, 11
	s_movk_i32 s27, 0x7fff
	v_writelane_b32 v252, s1, 51
	s_cselect_b64 s[0:1], -1, 0
	v_writelane_b32 v252, s0, 52
	s_cmp_eq_u32 s8, 10
	s_movk_i32 s68, 0x3000
	v_writelane_b32 v252, s1, 53
	s_cselect_b64 s[0:1], -1, 0
	v_writelane_b32 v252, s0, 54
	s_cmp_eq_u32 s8, 9
	s_mov_b32 s86, 0x5040100
	v_writelane_b32 v252, s1, 55
	s_cselect_b64 s[0:1], -1, 0
	v_writelane_b32 v252, s0, 56
	s_cmp_eq_u32 s8, 8
	s_mov_b32 s87, 0x800000
	v_writelane_b32 v252, s1, 57
	s_cselect_b64 s[0:1], -1, 0
	v_writelane_b32 v252, s0, 58
	s_cmp_eq_u32 s8, 7
	s_movk_i32 s91, 0xfff
	v_writelane_b32 v252, s1, 59
	s_cselect_b64 s[0:1], -1, 0
	v_writelane_b32 v252, s0, 60
	s_cmp_eq_u32 s8, 6
	s_movk_i32 s88, 0x1400
	v_writelane_b32 v252, s1, 61
	s_cselect_b64 s[0:1], -1, 0
	v_writelane_b32 v252, s0, 62
	s_cmp_eq_u32 s8, 5
	s_movk_i32 s89, 0x1ff
	v_writelane_b32 v252, s1, 63
	s_cselect_b64 s[0:1], -1, 0
	v_writelane_b32 v253, s0, 0
	s_cmp_eq_u32 s8, 4
	s_mov_b32 s36, 0x3f2aaaab
	v_writelane_b32 v253, s1, 1
	s_cselect_b64 s[0:1], -1, 0
	v_writelane_b32 v253, s0, 2
	s_cmp_eq_u32 s8, 3
	s_mov_b32 s78, 0x3f317218
	v_writelane_b32 v253, s1, 3
	s_cselect_b64 s[0:1], -1, 0
	v_writelane_b32 v253, s0, 4
	s_cmp_eq_u32 s8, 2
	s_mov_b32 s79, 0x7f800000
	v_writelane_b32 v253, s1, 5
	s_cselect_b64 s[0:1], -1, 0
	v_writelane_b32 v253, s0, 6
	s_cmp_eq_u32 s8, 1
	s_mov_b32 s33, 0x2aaaaaab
	v_writelane_b32 v253, s1, 7
	s_cselect_b64 s[0:1], -1, 0
	v_writelane_b32 v253, s0, 8
	s_cmp_eq_u32 s8, 0
	s_mov_b32 s31, 0
	v_writelane_b32 v253, s1, 9
	s_cselect_b64 s[0:1], -1, 0
	s_lshl_b32 s4, s8, 8
	s_add_u32 s2, s2, s4
	v_writelane_b32 v253, s0, 10
	s_addc_u32 s3, s3, 0
	s_mov_b64 s[34:35], 0x80
	v_writelane_b32 v253, s1, 11
	s_add_u32 s0, s2, 0x1400
	s_addc_u32 s1, s3, 0
	v_writelane_b32 v253, s0, 12
	v_readlane_b32 s2, v252, 3
	v_readlane_b32 s3, v252, 4
	v_writelane_b32 v253, s1, 13
	s_add_u32 s0, s12, 0x12cdb400
	s_addc_u32 s1, s13, 0
	v_writelane_b32 v253, s0, 14
	s_add_i32 s69, 0, 0x21fe0
	s_mov_b32 s26, 0x3dd53b94
	v_writelane_b32 v253, s1, 15
	v_readlane_b32 s0, v252, 1
	v_readlane_b32 s1, v252, 2
	s_mul_i32 s0, s1, s0
	s_load_dword s1, s[2:3], 0x158
	s_mov_b32 s2, 0x33800000
	s_mov_b64 s[94:95], 0x400
	s_mov_b64 s[60:61], 0x1000
	s_mov_b32 s28, 0x3e0293ee
	s_waitcnt lgkmcnt(0)
	s_mul_i32 s0, s0, s1
	v_writelane_b32 v253, s0, 16
	s_add_i32 s0, 0, 0x20000
	v_writelane_b32 v253, s0, 17
	s_add_i32 s0, 0, 0x7fbe
	v_writelane_b32 v253, s0, 18
	s_add_i32 s0, 0, 0x13800
	v_writelane_b32 v253, s0, 19
	s_add_i32 s0, 0, 0x19000
	v_writelane_b32 v253, s0, 20
	s_add_i32 s0, 0, 0x17000
	v_writelane_b32 v253, s0, 21
	s_add_i32 s0, 0, 0xd00
	v_writelane_b32 v253, s0, 22
	s_add_i32 s0, 0, 0x21ff0
	v_writelane_b32 v253, s0, 23
	s_add_i32 s0, 0, 0x21ff4
	v_writelane_b32 v253, s0, 24
	v_cmp_eq_u32_e64 s[0:1], 0, v0
	s_nop 1
	v_writelane_b32 v253, s0, 25
	s_nop 1
	v_writelane_b32 v253, s1, 26
	v_writelane_b32 v253, s69, 27
	v_writelane_b32 v253, s92, 28
	s_nop 1
	v_writelane_b32 v253, s93, 29
	s_branch .LBB0_13

.LBB0_103:
	v_readlane_b32 s3, v252, 0
	s_nop 1
	s_lshr_b32 s4, s3, 4
	s_and_b32 s5, s3, 15
	s_lshr_b32 s6, s4, 1
	s_and_b32 s7, s4, 1
	s_mul_i32 s6, s6, 0x42
	s_addk_i32 s6, 0x40
	s_add_i32 s6, s6, s7
	s_cmpk_ge_u32 s6, 0xb0
	s_cselect_b32 s98, 1, 0
	s_cmpk_ge_u32 s6, 0x160
	s_cselect_b32 s98, 2, s98
	s_mul_i32 s99, s98, 0xb0
	s_sub_i32 s6, s6, s99
	s_and_b32 s7, s6, 7
	s_lshl_b32 s98, s98, 3
	s_add_i32 s98, s98, s7
	s_lshr_b32 s99, s6, 3
	s_lshr_b32 s6, s5, 2
	s_and_b32 s7, s5, 3
	s_lshl_b32 s98, s98, 8
	s_lshl_b32 s6, s6, 6
	s_add_i32 s98, s98, s6
	v_and_b32_e32 v238, 31, v202
	v_lshrrev_b32_e32 v239, 6, v202
	v_bfe_u32 v240, v202, 5, 1
	v_lshlrev_b32_e32 v236, 11, v238
	v_lshl_add_u32 v236, v239, 8, v236
	v_lshl_add_u32 v236, v240, 4, v236
	v_mov_b32_e32 v237, 0
	s_add_u32 s100, s80, 0x1800000
	s_addc_u32 s101, s81, 0
	s_lshl_b32 s6, s98, 11
	s_add_u32 s100, s100, s6
	s_addc_u32 s101, s101, 0
	v_lshl_add_u64 v[228:229], s[100:101], 0, v[236:237]
	v_add_co_u32_e32 v230, vcc, 0x10000, v228
	s_nop 1
	v_addc_co_u32_e32 v231, vcc, 0, v229, vcc
	s_mul_i32 s6, s46, 0xb00000
	s_add_u32 s100, s80, 0x8be8000
	s_addc_u32 s101, s81, 0
	s_add_u32 s100, s100, s6
	s_addc_u32 s101, s101, 0
	s_lshl_b32 s6, s99, 19
	s_lshl_b32 s4, s7, 16
	s_add_i32 s6, s6, s4
	s_add_u32 s100, s100, s6
	s_addc_u32 s101, s101, 0
	v_lshl_add_u64 v[232:233], s[100:101], 0, v[236:237]
	v_add_co_u32_e32 v234, vcc, 0x40000, v232
	s_nop 1
	v_addc_co_u32_e32 v235, vcc, 0, v233, vcc
	global_load_dwordx4 v[66:69], v[228:229], off
	global_load_dwordx4 v[70:73], v[230:231], off
	global_load_dwordx4 v[130:133], v[232:233], off
	global_load_dwordx4 v[134:137], v[234:235], off
	global_load_dwordx4 v[74:77], v[228:229], off offset:32
	global_load_dwordx4 v[78:81], v[230:231], off offset:32
	global_load_dwordx4 v[138:141], v[232:233], off offset:32
	global_load_dwordx4 v[142:145], v[234:235], off offset:32
	global_load_dwordx4 v[82:85], v[228:229], off offset:64
	global_load_dwordx4 v[86:89], v[230:231], off offset:64
	global_load_dwordx4 v[146:149], v[232:233], off offset:64
	global_load_dwordx4 v[150:153], v[234:235], off offset:64
	global_load_dwordx4 v[90:93], v[228:229], off offset:96
	global_load_dwordx4 v[94:97], v[230:231], off offset:96
	global_load_dwordx4 v[154:157], v[232:233], off offset:96
	global_load_dwordx4 v[158:161], v[234:235], off offset:96
	global_load_dwordx4 v[98:101], v[228:229], off offset:128
	global_load_dwordx4 v[102:105], v[230:231], off offset:128
	global_load_dwordx4 v[162:165], v[232:233], off offset:128
	global_load_dwordx4 v[166:169], v[234:235], off offset:128
	global_load_dwordx4 v[106:109], v[228:229], off offset:160
	global_load_dwordx4 v[110:113], v[230:231], off offset:160
	global_load_dwordx4 v[176:179], v[232:233], off offset:160
	global_load_dwordx4 v[180:183], v[234:235], off offset:160
	global_load_dwordx4 v[114:117], v[228:229], off offset:192
	global_load_dwordx4 v[118:121], v[230:231], off offset:192
	global_load_dwordx4 v[184:187], v[232:233], off offset:192
	global_load_dwordx4 v[188:191], v[234:235], off offset:192
	global_load_dwordx4 v[122:125], v[228:229], off offset:224
	global_load_dwordx4 v[126:129], v[230:231], off offset:224
	global_load_dwordx4 v[192:195], v[232:233], off offset:224
	global_load_dwordx4 v[196:199], v[234:235], off offset:224
	v_mov_b32_e32 v2, 0
	v_mov_b32_e32 v3, 0
	v_mov_b32_e32 v4, 0
	v_mov_b32_e32 v5, 0
	v_mov_b32_e32 v6, 0
	v_mov_b32_e32 v7, 0
	v_mov_b32_e32 v8, 0
	v_mov_b32_e32 v9, 0
	v_mov_b32_e32 v10, 0
	v_mov_b32_e32 v11, 0
	v_mov_b32_e32 v12, 0
	v_mov_b32_e32 v13, 0
	v_mov_b32_e32 v14, 0
	v_mov_b32_e32 v15, 0
	v_mov_b32_e32 v16, 0
	v_mov_b32_e32 v17, 0
	v_mov_b32_e32 v18, 0
	v_mov_b32_e32 v19, 0
	v_mov_b32_e32 v20, 0
	v_mov_b32_e32 v21, 0
	v_mov_b32_e32 v22, 0
	v_mov_b32_e32 v23, 0
	v_mov_b32_e32 v24, 0
	v_mov_b32_e32 v25, 0
	v_mov_b32_e32 v26, 0
	v_mov_b32_e32 v27, 0
	v_mov_b32_e32 v28, 0
	v_mov_b32_e32 v29, 0
	v_mov_b32_e32 v30, 0
	v_mov_b32_e32 v31, 0
	v_mov_b32_e32 v32, 0
	v_mov_b32_e32 v33, 0
	v_mov_b32_e32 v34, 0
	v_mov_b32_e32 v35, 0
	v_mov_b32_e32 v36, 0
	v_mov_b32_e32 v37, 0
	v_mov_b32_e32 v38, 0
	v_mov_b32_e32 v39, 0
	v_mov_b32_e32 v40, 0
	v_mov_b32_e32 v41, 0
	v_mov_b32_e32 v42, 0
	v_mov_b32_e32 v43, 0
	v_mov_b32_e32 v44, 0
	v_mov_b32_e32 v45, 0
	v_mov_b32_e32 v46, 0
	v_mov_b32_e32 v47, 0
	v_mov_b32_e32 v48, 0
	v_mov_b32_e32 v49, 0
	v_mov_b32_e32 v50, 0
	v_mov_b32_e32 v51, 0
	v_mov_b32_e32 v52, 0
	v_mov_b32_e32 v53, 0
	v_mov_b32_e32 v54, 0
	v_mov_b32_e32 v55, 0
	v_mov_b32_e32 v56, 0
	v_mov_b32_e32 v57, 0
	v_mov_b32_e32 v58, 0
	v_mov_b32_e32 v59, 0
	v_mov_b32_e32 v60, 0
	v_mov_b32_e32 v61, 0
	v_mov_b32_e32 v62, 0
	v_mov_b32_e32 v63, 0
	v_mov_b32_e32 v64, 0
	v_mov_b32_e32 v65, 0
	s_add_u32 s100, s80, 0x4f28000
	s_addc_u32 s101, s81, 0
	s_mul_i32 s6, s98, 0x1600
	s_add_u32 s100, s100, s6
	s_addc_u32 s101, s101, 0
	s_lshl_b32 s6, s99, 8
	s_lshl_b32 s4, s7, 6
	s_add_i32 s6, s6, s4
	s_add_u32 s100, s100, s6
	s_addc_u32 s101, s101, 0
	s_waitcnt vmcnt(28)
	v_mfma_f32_32x32x16_bf16 v[2:17], v[66:69], v[130:133], v[2:17]
	v_mfma_f32_32x32x16_bf16 v[18:33], v[66:69], v[134:137], v[18:33]
	v_mfma_f32_32x32x16_bf16 v[34:49], v[70:73], v[130:133], v[34:49]
	v_mfma_f32_32x32x16_bf16 v[50:65], v[70:73], v[134:137], v[50:65]
	s_waitcnt vmcnt(24)
	v_mfma_f32_32x32x16_bf16 v[2:17], v[74:77], v[138:141], v[2:17]
	v_mfma_f32_32x32x16_bf16 v[18:33], v[74:77], v[142:145], v[18:33]
	v_mfma_f32_32x32x16_bf16 v[34:49], v[78:81], v[138:141], v[34:49]
	v_mfma_f32_32x32x16_bf16 v[50:65], v[78:81], v[142:145], v[50:65]
	s_waitcnt vmcnt(20)
	v_mfma_f32_32x32x16_bf16 v[2:17], v[82:85], v[146:149], v[2:17]
	v_mfma_f32_32x32x16_bf16 v[18:33], v[82:85], v[150:153], v[18:33]
	v_mfma_f32_32x32x16_bf16 v[34:49], v[86:89], v[146:149], v[34:49]
	v_mfma_f32_32x32x16_bf16 v[50:65], v[86:89], v[150:153], v[50:65]
	s_waitcnt vmcnt(16)
	v_mfma_f32_32x32x16_bf16 v[2:17], v[90:93], v[154:157], v[2:17]
	v_mfma_f32_32x32x16_bf16 v[18:33], v[90:93], v[158:161], v[18:33]
	v_mfma_f32_32x32x16_bf16 v[34:49], v[94:97], v[154:157], v[34:49]
	v_mfma_f32_32x32x16_bf16 v[50:65], v[94:97], v[158:161], v[50:65]
	s_waitcnt vmcnt(12)
	v_mfma_f32_32x32x16_bf16 v[2:17], v[98:101], v[162:165], v[2:17]
	v_mfma_f32_32x32x16_bf16 v[18:33], v[98:101], v[166:169], v[18:33]
	v_mfma_f32_32x32x16_bf16 v[34:49], v[102:105], v[162:165], v[34:49]
	v_mfma_f32_32x32x16_bf16 v[50:65], v[102:105], v[166:169], v[50:65]
	s_waitcnt vmcnt(8)
	v_mfma_f32_32x32x16_bf16 v[2:17], v[106:109], v[176:179], v[2:17]
	v_mfma_f32_32x32x16_bf16 v[18:33], v[106:109], v[180:183], v[18:33]
	v_mfma_f32_32x32x16_bf16 v[34:49], v[110:113], v[176:179], v[34:49]
	v_mfma_f32_32x32x16_bf16 v[50:65], v[110:113], v[180:183], v[50:65]
	s_waitcnt vmcnt(4)
	v_mfma_f32_32x32x16_bf16 v[2:17], v[114:117], v[184:187], v[2:17]
	v_mfma_f32_32x32x16_bf16 v[18:33], v[114:117], v[188:191], v[18:33]
	v_mfma_f32_32x32x16_bf16 v[34:49], v[118:121], v[184:187], v[34:49]
	v_mfma_f32_32x32x16_bf16 v[50:65], v[118:121], v[188:191], v[50:65]
	s_waitcnt vmcnt(0)
	v_mfma_f32_32x32x16_bf16 v[2:17], v[122:125], v[192:195], v[2:17]
	v_mfma_f32_32x32x16_bf16 v[18:33], v[122:125], v[196:199], v[18:33]
	v_mfma_f32_32x32x16_bf16 v[34:49], v[126:129], v[192:195], v[34:49]
	v_mfma_f32_32x32x16_bf16 v[50:65], v[126:129], v[196:199], v[50:65]
	v_and_b32_e32 v241, 63, v202
	v_lshlrev_b32_e32 v242, 2, v241
	v_lshl_add_u32 v242, v239, 14, v242
	s_nop 15
	ds_write2st64_b32 v242, v2, v3 offset1:1
	ds_write2st64_b32 v242, v4, v5 offset0:2 offset1:3
	ds_write2st64_b32 v242, v6, v7 offset0:4 offset1:5
	ds_write2st64_b32 v242, v8, v9 offset0:6 offset1:7
	ds_write2st64_b32 v242, v10, v11 offset0:8 offset1:9
	ds_write2st64_b32 v242, v12, v13 offset0:10 offset1:11
	ds_write2st64_b32 v242, v14, v15 offset0:12 offset1:13
	ds_write2st64_b32 v242, v16, v17 offset0:14 offset1:15
	ds_write2st64_b32 v242, v18, v19 offset0:16 offset1:17
	ds_write2st64_b32 v242, v20, v21 offset0:18 offset1:19
	ds_write2st64_b32 v242, v22, v23 offset0:20 offset1:21
	ds_write2st64_b32 v242, v24, v25 offset0:22 offset1:23
	ds_write2st64_b32 v242, v26, v27 offset0:24 offset1:25
	ds_write2st64_b32 v242, v28, v29 offset0:26 offset1:27
	ds_write2st64_b32 v242, v30, v31 offset0:28 offset1:29
	ds_write2st64_b32 v242, v32, v33 offset0:30 offset1:31
	ds_write2st64_b32 v242, v34, v35 offset0:32 offset1:33
	ds_write2st64_b32 v242, v36, v37 offset0:34 offset1:35
	ds_write2st64_b32 v242, v38, v39 offset0:36 offset1:37
	ds_write2st64_b32 v242, v40, v41 offset0:38 offset1:39
	ds_write2st64_b32 v242, v42, v43 offset0:40 offset1:41
	ds_write2st64_b32 v242, v44, v45 offset0:42 offset1:43
	ds_write2st64_b32 v242, v46, v47 offset0:44 offset1:45
	ds_write2st64_b32 v242, v48, v49 offset0:46 offset1:47
	ds_write2st64_b32 v242, v50, v51 offset0:48 offset1:49
	ds_write2st64_b32 v242, v52, v53 offset0:50 offset1:51
	ds_write2st64_b32 v242, v54, v55 offset0:52 offset1:53
	ds_write2st64_b32 v242, v56, v57 offset0:54 offset1:55
	ds_write2st64_b32 v242, v58, v59 offset0:56 offset1:57
	ds_write2st64_b32 v242, v60, v61 offset0:58 offset1:59
	ds_write2st64_b32 v242, v62, v63 offset0:60 offset1:61
	ds_write2st64_b32 v242, v64, v65 offset0:62 offset1:63
	s_waitcnt lgkmcnt(0)
	s_barrier
	v_lshrrev_b32_e32 v243, 2, v239
	v_and_b32_e32 v244, 3, v239
	v_lshlrev_b32_e32 v245, 13, v243
	v_lshl_add_u32 v245, v244, 10, v245
	v_lshl_add_u32 v245, v241, 2, v245
	v_add_u32_e32 v246, 0x10000, v245
	v_lshlrev_b32_e32 v248, 5, v243
	v_lshl_add_u32 v248, v244, 3, v248
	v_lshl_add_u32 v248, v240, 2, v248
	v_mul_u32_u24_e32 v248, 0x1600, v248
	v_lshl_add_u32 v248, v238, 1, v248
	v_mov_b32_e32 v249, 0
	v_lshl_add_u64 v[250:251], s[100:101], 0, v[248:249]
	ds_read2st64_b32 v[66:67], v245 offset0:0 offset1:64
	ds_read2st64_b32 v[68:69], v245 offset0:128 offset1:192
	ds_read2st64_b32 v[70:71], v246 offset0:0 offset1:64
	ds_read2st64_b32 v[72:73], v246 offset0:128 offset1:192
	ds_read2st64_b32 v[74:75], v245 offset0:16 offset1:80
	ds_read2st64_b32 v[76:77], v245 offset0:144 offset1:208
	ds_read2st64_b32 v[78:79], v246 offset0:16 offset1:80
	ds_read2st64_b32 v[80:81], v246 offset0:144 offset1:208
	s_waitcnt lgkmcnt(0)
	v_add_f32_e32 v66, v66, v67
	v_add_f32_e32 v68, v68, v69
	v_add_f32_e32 v70, v70, v71
	v_add_f32_e32 v72, v72, v73
	v_add_f32_e32 v66, v66, v68
	v_add_f32_e32 v70, v70, v72
	v_add_f32_e32 v66, v66, v70
	v_add_f32_e32 v74, v74, v75
	v_add_f32_e32 v76, v76, v77
	v_add_f32_e32 v78, v78, v79
	v_add_f32_e32 v80, v80, v81
	v_add_f32_e32 v74, v74, v76
	v_add_f32_e32 v78, v78, v80
	v_add_f32_e32 v74, v74, v78
	v_mul_f32_e32 v82, 0xbfb8aa3b, v66
	v_exp_f32_e32 v82, v82
	s_nop 0
	v_add_f32_e32 v82, 1.0, v82
	v_rcp_f32_e32 v82, v82
	s_nop 0
	v_mul_f32_e32 v82, v66, v82
	v_mul_f32_e32 v82, v82, v74
	v_cvt_pk_bf16_f32 v83, v82, v82
	global_store_short v[250:251], v83, off
	ds_read2st64_b32 v[66:67], v245 offset0:1 offset1:65
	ds_read2st64_b32 v[68:69], v245 offset0:129 offset1:193
	ds_read2st64_b32 v[70:71], v246 offset0:1 offset1:65
	ds_read2st64_b32 v[72:73], v246 offset0:129 offset1:193
	ds_read2st64_b32 v[74:75], v245 offset0:17 offset1:81
	ds_read2st64_b32 v[76:77], v245 offset0:145 offset1:209
	ds_read2st64_b32 v[78:79], v246 offset0:17 offset1:81
	ds_read2st64_b32 v[80:81], v246 offset0:145 offset1:209
	s_waitcnt lgkmcnt(0)
	v_add_f32_e32 v66, v66, v67
	v_add_f32_e32 v68, v68, v69
	v_add_f32_e32 v70, v70, v71
	v_add_f32_e32 v72, v72, v73
	v_add_f32_e32 v66, v66, v68
	v_add_f32_e32 v70, v70, v72
	v_add_f32_e32 v66, v66, v70
	v_add_f32_e32 v74, v74, v75
	v_add_f32_e32 v76, v76, v77
	v_add_f32_e32 v78, v78, v79
	v_add_f32_e32 v80, v80, v81
	v_add_f32_e32 v74, v74, v76
	v_add_f32_e32 v78, v78, v80
	v_add_f32_e32 v74, v74, v78
	v_mul_f32_e32 v82, 0xbfb8aa3b, v66
	v_exp_f32_e32 v82, v82
	s_nop 0
	v_add_f32_e32 v82, 1.0, v82
	v_rcp_f32_e32 v82, v82
	s_nop 0
	v_mul_f32_e32 v82, v66, v82
	v_mul_f32_e32 v82, v82, v74
	v_cvt_pk_bf16_f32 v83, v82, v82
	v_add_co_u32_e32 v84, vcc, 5632, v250
	s_nop 1
	v_addc_co_u32_e32 v85, vcc, 0, v251, vcc
	global_store_short v[84:85], v83, off
	ds_read2st64_b32 v[66:67], v245 offset0:2 offset1:66
	ds_read2st64_b32 v[68:69], v245 offset0:130 offset1:194
	ds_read2st64_b32 v[70:71], v246 offset0:2 offset1:66
	ds_read2st64_b32 v[72:73], v246 offset0:130 offset1:194
	ds_read2st64_b32 v[74:75], v245 offset0:18 offset1:82
	ds_read2st64_b32 v[76:77], v245 offset0:146 offset1:210
	ds_read2st64_b32 v[78:79], v246 offset0:18 offset1:82
	ds_read2st64_b32 v[80:81], v246 offset0:146 offset1:210
	s_waitcnt lgkmcnt(0)
	v_add_f32_e32 v66, v66, v67
	v_add_f32_e32 v68, v68, v69
	v_add_f32_e32 v70, v70, v71
	v_add_f32_e32 v72, v72, v73
	v_add_f32_e32 v66, v66, v68
	v_add_f32_e32 v70, v70, v72
	v_add_f32_e32 v66, v66, v70
	v_add_f32_e32 v74, v74, v75
	v_add_f32_e32 v76, v76, v77
	v_add_f32_e32 v78, v78, v79
	v_add_f32_e32 v80, v80, v81
	v_add_f32_e32 v74, v74, v76
	v_add_f32_e32 v78, v78, v80
	v_add_f32_e32 v74, v74, v78
	v_mul_f32_e32 v82, 0xbfb8aa3b, v66
	v_exp_f32_e32 v82, v82
	s_nop 0
	v_add_f32_e32 v82, 1.0, v82
	v_rcp_f32_e32 v82, v82
	s_nop 0
	v_mul_f32_e32 v82, v66, v82
	v_mul_f32_e32 v82, v82, v74
	v_cvt_pk_bf16_f32 v83, v82, v82
	v_add_co_u32_e32 v84, vcc, 11264, v250
	s_nop 1
	v_addc_co_u32_e32 v85, vcc, 0, v251, vcc
	global_store_short v[84:85], v83, off
	ds_read2st64_b32 v[66:67], v245 offset0:3 offset1:67
	ds_read2st64_b32 v[68:69], v245 offset0:131 offset1:195
	ds_read2st64_b32 v[70:71], v246 offset0:3 offset1:67
	ds_read2st64_b32 v[72:73], v246 offset0:131 offset1:195
	ds_read2st64_b32 v[74:75], v245 offset0:19 offset1:83
	ds_read2st64_b32 v[76:77], v245 offset0:147 offset1:211
	ds_read2st64_b32 v[78:79], v246 offset0:19 offset1:83
	ds_read2st64_b32 v[80:81], v246 offset0:147 offset1:211
	s_waitcnt lgkmcnt(0)
	v_add_f32_e32 v66, v66, v67
	v_add_f32_e32 v68, v68, v69
	v_add_f32_e32 v70, v70, v71
	v_add_f32_e32 v72, v72, v73
	v_add_f32_e32 v66, v66, v68
	v_add_f32_e32 v70, v70, v72
	v_add_f32_e32 v66, v66, v70
	v_add_f32_e32 v74, v74, v75
	v_add_f32_e32 v76, v76, v77
	v_add_f32_e32 v78, v78, v79
	v_add_f32_e32 v80, v80, v81
	v_add_f32_e32 v74, v74, v76
	v_add_f32_e32 v78, v78, v80
	v_add_f32_e32 v74, v74, v78
	v_mul_f32_e32 v82, 0xbfb8aa3b, v66
	v_exp_f32_e32 v82, v82
	s_nop 0
	v_add_f32_e32 v82, 1.0, v82
	v_rcp_f32_e32 v82, v82
	s_nop 0
	v_mul_f32_e32 v82, v66, v82
	v_mul_f32_e32 v82, v82, v74
	v_cvt_pk_bf16_f32 v83, v82, v82
	v_add_co_u32_e32 v84, vcc, 16896, v250
	s_nop 1
	v_addc_co_u32_e32 v85, vcc, 0, v251, vcc
	global_store_short v[84:85], v83, off
	s_waitcnt lgkmcnt(0)
	s_barrier
	v_readlane_b32 s4, v254, 14
	v_readlane_b32 s5, v254, 15
	s_andn2_b64 vcc, exec, s[4:5]
	s_cbranch_vccnz .LBB0_494
	s_add_u32 s3, s80, 0x8628000
	s_addc_u32 s6, s81, 0
	s_mov_b64 s[14:15], -1
	s_and_b64 vcc, exec, s[0:1]
	s_cbranch_vccz .LBB0_298
	s_abs_i32 s10, s72
	v_cvt_f32_u32_e32 v0, s10
	s_load_dwordx8 s[44:51], s[8:9], 0x110
	s_load_dwordx2 s[0:1], s[8:9], 0x100
	s_load_dwordx4 s[52:55], s[8:9], 0xa0
	s_load_dwordx2 s[22:23], s[8:9], 0x60
	s_sub_i32 s4, 0, s10
	s_add_i32 s7, s72, s70
	v_rcp_iflag_f32_e32 v0, v0
	s_mov_b32 s11, 0
	s_lshl_b32 s19, s72, 8
	s_mov_b32 s20, 0
	v_mul_f32_e32 v0, 0x4f7ffffe, v0
	v_cvt_u32_f32_e32 v0, v0
	s_nop 0
	v_readfirstlane_b32 s5, v0
	s_mul_i32 s4, s4, s5
	s_mul_hi_u32 s4, s5, s4
	s_add_i32 s18, s5, s4
	s_branch .LBB0_108

	.amdhsa_kernel _Z4mega6Params
		.amdhsa_group_segment_fixed_size 0
		.amdhsa_private_segment_fixed_size 0
		.amdhsa_kernarg_size 592
		.amdhsa_user_sgpr_count 2
		.amdhsa_user_sgpr_dispatch_ptr 0
		.amdhsa_user_sgpr_queue_ptr 0
		.amdhsa_user_sgpr_kernarg_segment_ptr 1
		.amdhsa_user_sgpr_dispatch_id 0
		.amdhsa_user_sgpr_kernarg_preload_length 0
		.amdhsa_user_sgpr_kernarg_preload_offset 0
		.amdhsa_user_sgpr_private_segment_size 0
		.amdhsa_uses_dynamic_stack 0
		.amdhsa_enable_private_segment 0
		.amdhsa_system_sgpr_workgroup_id_x 1
		.amdhsa_system_sgpr_workgroup_id_y 0
		.amdhsa_system_sgpr_workgroup_id_z 0
		.amdhsa_system_sgpr_workgroup_info 0
		.amdhsa_system_vgpr_workitem_id 2
		.amdhsa_next_free_vgpr 256
		.amdhsa_next_free_sgpr 102
		.amdhsa_accum_offset 256
		.amdhsa_reserve_vcc 1
		.amdhsa_float_round_mode_32 0
		.amdhsa_float_round_mode_16_64 0
		.amdhsa_float_denorm_mode_32 3
		.amdhsa_float_denorm_mode_16_64 3
		.amdhsa_dx10_clamp 1
		.amdhsa_ieee_mode 1
		.amdhsa_fp16_overflow 0
		.amdhsa_tg_split 0
		.amdhsa_exception_fp_ieee_invalid_op 0
		.amdhsa_exception_fp_denorm_src 0
		.amdhsa_exception_fp_ieee_div_zero 0
		.amdhsa_exception_fp_ieee_overflow 0
		.amdhsa_exception_fp_ieee_underflow 0
		.amdhsa_exception_fp_ieee_inexact 0
		.amdhsa_exception_int_div_zero 0
	.end_amdhsa_kernel

amdhsa.kernels:
  - .agpr_count:     0
    .args:
      - .offset:         0
        .size:           336
        .value_kind:     by_value
      - .offset:         336
        .size:           4
        .value_kind:     hidden_block_count_x
      - .offset:         340
        .size:           4
        .value_kind:     hidden_block_count_y
      - .offset:         344
        .size:           4
        .value_kind:     hidden_block_count_z
      - .offset:         348
        .size:           2
        .value_kind:     hidden_group_size_x
      - .offset:         350
        .size:           2
        .value_kind:     hidden_group_size_y
      - .offset:         352
        .size:           2
        .value_kind:     hidden_group_size_z
      - .offset:         354
        .size:           2
        .value_kind:     hidden_remainder_x
      - .offset:         356
        .size:           2
        .value_kind:     hidden_remainder_y
      - .offset:         358
        .size:           2
        .value_kind:     hidden_remainder_z
      - .offset:         376
        .size:           8
        .value_kind:     hidden_global_offset_x
      - .offset:         384
        .size:           8
        .value_kind:     hidden_global_offset_y
      - .offset:         392
        .size:           8
        .value_kind:     hidden_global_offset_z
      - .offset:         400
        .size:           2
        .value_kind:     hidden_grid_dims
      - .offset:         424
        .size:           8
        .value_kind:     hidden_multigrid_sync_arg
      - .offset:         456
        .size:           4
        .value_kind:     hidden_dynamic_lds_size
    .group_segment_fixed_size: 0
    .kernarg_segment_align: 8
    .kernarg_segment_size: 592
    .language:       OpenCL C
    .language_version:
      - 2
      - 0
    .max_flat_workgroup_size: 512
    .name:           _Z4mega6Params
    .private_segment_fixed_size: 0
    .sgpr_count:     108
    .sgpr_spill_count: 243
    .symbol:         _Z4mega6Params.kd
    .uniform_work_group_size: 1
    .uses_dynamic_stack: false
    .vgpr_count:     256
    .vgpr_spill_count: 0
    .wavefront_size: 64
